# G1 K-loop: first half-trip after an epilogue peeled, its two DMA waits counted past the epilogue's 16 stores (vmcnt 24)
# speedup vs baseline: 1.0043x; 1.0043x over previous
; #define PG8_STAGE(bufoff, gbase, voff) do { _Pragma("unroll") for (int _i = 0; _i < 2; ++_i) \
;         __builtin_amdgcn_global_load_lds((const unsigned*)((const char*)(gbase) + (voff)[_i]), (LAS unsigned*)(lds + (bufoff) + ldsw + _i * 8192), 16, 0, 0); } while (0)
; #define PG8_LDA(dst, b, h) do { _Pragma("unroll") for (int m = 0; m < 4; ++m) _Pragma("unroll") for (int k = 0; k < 2; ++k) dst[m][k] = *(const LAS h8*)(lds + PG8_SA(b, h) + aoff + m * 2048 + k * 1024); } while (0)
; #define PG8_LDB(dst, b, h) do { _Pragma("unroll") for (int n = 0; n < 2; ++n) _Pragma("unroll") for (int k = 0; k < 2; ++k) dst[n][k] = *(const LAS h8*)(lds + PG8_SB(b, h) + boff + n * 2048 + k * 1024); } while (0)
; #define PG8_MMA(ai, bj, At, Bt) do { __builtin_amdgcn_s_setprio(1); _Pragma("unroll") for (int m = 0; m < 4; ++m) _Pragma("unroll") for (int n = 0; n < 2; ++n) _Pragma("unroll") for (int k = 0; k < 2; ++k) \
;         acc[ai][bj][m][n] = __builtin_amdgcn_mfma_f32_16x16x32_f16(Bt[n][k], At[m][k], acc[ai][bj][m][n], 0, 0, 0); __builtin_amdgcn_s_setprio(0); } while (0)
; #define PG8_WAIT_V(n) asm volatile("s_waitcnt vmcnt(" #n ")" ::: "memory")
; #define PG8_WAIT_L(n) asm volatile("s_waitcnt lgkmcnt(" #n ")" ::: "memory")
; #define PG8_BAR __builtin_amdgcn_s_barrier()
; #define PG8_SCHED __builtin_amdgcn_sched_barrier(0)
; template <class Epi>
; __device__ __forceinline__ void gemm_phase(LAS unsigned char* lds, const Gemm g, const StaticOrder& S, const Epi& E, unsigned long long& sw_acc) {
;     ...
;         const bool has_next = S.next(ui + 1, nxt);
;         const char* nA = has_next ? (const char*)g.A + (size_t)nxt.pm * tstep : cA; const char* nB = has_next ? (const char*)g.Bt + (size_t)nxt.pn * tstep : cB;
;         for (int t = 0; t < nt; t += 2) {
;             const bool last = (t == nt - 2);
;             const char* a1 = cA + (size_t)(t + 1) * kstepA;
;             const char* a2 = last ? nA : cA + (size_t)(t + 2) * kstepA; const char* b2 = last ? nB : cB + (size_t)(t + 2) * kstep;
;             const char* a3 = a2 + kstepA; const char* b3 = b2 + kstep;
;             PG8_LDB(B0, 0, 0); PG8_LDB(B1, 0, 1); PG8_SCHED; PG8_LDA(At, 0, 0); PG8_STAGE(PG8_SA(1, 1), a1 + hstep, voffA);
;             PG8_WAIT_V(8); PG8_WAIT_L(0); PG8_BAR; PG8_MMA(0, 0, At, B0); PG8_MMA(0, 1, At, B1); PG8_BAR; PG8_SCHED;
.LBB0_133:
	s_xor_b64 s[60:61], s[66:67], -1
	s_add_u32 s72, s4, 0x100
	s_mov_b32 s56, s0
	s_addc_u32 s73, s5, 0
	s_ashr_i32 s57, s0, 31
	s_mov_b32 s58, s1
	s_lshl_b64 s[0:1], s[56:57], 19
	s_add_u32 s64, s48, s0
	s_addc_u32 s65, s49, s1
	s_and_b64 s[0:1], s[66:67], exec
	s_cselect_b32 s0, s65, s53
	s_cselect_b32 s1, s64, s52
	s_ashr_i32 s59, s58, 31
	s_lshl_b64 s[6:7], s[58:59], 19
	s_add_u32 s62, s27, s6
	s_addc_u32 s63, s30, s7
	s_and_b64 s[6:7], s[66:67], exec
	s_cselect_b32 s10, s63, s5
	s_cselect_b32 s11, s62, s4
	s_add_u32 s4, s52, 0x40080
	s_addc_u32 s5, s53, 0
	v_lshl_add_u64 v[132:133], s[4:5], 0, v[202:203]
	v_lshl_add_u64 v[134:135], s[4:5], 0, v[204:205]
	s_mov_b32 s14, -2
	s_mov_b64 s[4:5], 0
	s_cmp_lg_u32 s70, 0
	s_cbranch_scc0 .LBB0_134
.Lg1_peel:
	s_add_u32 s6, s52, s4
	s_addc_u32 s7, s53, s5
	s_add_u32 s6, s6, 0x100
	s_addc_u32 s7, s7, 0
	s_add_u32 s15, s72, s4
	s_addc_u32 s20, s73, s5
	s_add_i32 s21, 0, 0x10000
	s_cmpk_eq_i32 s4, 0x700
	s_cselect_b32 s19, s0, s7
	s_cselect_b32 s18, s1, s6
	v_add_u32_e32 v2, s21, v218
	s_cselect_b32 s7, s10, s20
	s_cselect_b32 s6, s11, s15
	s_add_i32 s15, 0, 0x14000
	ds_read_b128 v[136:139], v2
	ds_read_b128 v[140:143], v2 offset:1024
	ds_read_b128 v[144:147], v2 offset:2048
	ds_read_b128 v[148:151], v2 offset:3072
	v_add_u32_e32 v2, s15, v218
	ds_read_b128 v[152:155], v2
	ds_read_b128 v[156:159], v2 offset:1024
	ds_read_b128 v[160:163], v2 offset:2048
	ds_read_b128 v[164:167], v2 offset:3072
	v_lshl_add_u64 v[240:241], v[132:133], 0, s[4:5]
	s_add_i32 m0, s31, 0xc000
	ds_read_b128 v[168:171], v221
	ds_read_b128 v[172:175], v221 offset:1024
	ds_read_b128 v[176:179], v221 offset:2048
	ds_read_b128 v[206:209], v221 offset:3072
	ds_read_b128 v[224:227], v221 offset:4096
	ds_read_b128 v[228:231], v221 offset:5120
	ds_read_b128 v[232:235], v221 offset:6144
	ds_read_b128 v[236:239], v221 offset:7168
	global_load_lds_dwordx4 v[240:241], off
	v_lshl_add_u64 v[240:241], v[134:135], 0, s[4:5]
	s_add_i32 m0, s31, 0xe000
	s_nop 0
	global_load_lds_dwordx4 v[240:241], off
	s_waitcnt vmcnt(24)
	s_waitcnt lgkmcnt(0)
	s_barrier
	s_setprio 1
	s_waitcnt lgkmcnt(0)
	v_mfma_f32_16x16x32_f16 v[128:131], v[136:139], v[168:171], v[128:131]
	v_mfma_f32_16x16x32_f16 v[124:127], v[144:147], v[168:171], v[124:127]
	v_mfma_f32_16x16x32_f16 v[120:123], v[136:139], v[176:179], v[120:123]
	v_mfma_f32_16x16x32_f16 v[116:119], v[144:147], v[176:179], v[116:119]
	v_mfma_f32_16x16x32_f16 v[112:115], v[136:139], v[224:227], v[112:115]
	v_mfma_f32_16x16x32_f16 v[108:111], v[144:147], v[224:227], v[108:111]
	v_mfma_f32_16x16x32_f16 v[104:107], v[136:139], v[232:235], v[104:107]
	v_mfma_f32_16x16x32_f16 v[100:103], v[144:147], v[232:235], v[100:103]
	v_mfma_f32_16x16x32_f16 v[128:131], v[140:143], v[172:175], v[128:131]
	v_mfma_f32_16x16x32_f16 v[124:127], v[148:151], v[172:175], v[124:127]
	v_mfma_f32_16x16x32_f16 v[120:123], v[140:143], v[206:209], v[120:123]
	v_mfma_f32_16x16x32_f16 v[116:119], v[148:151], v[206:209], v[116:119]
	v_mfma_f32_16x16x32_f16 v[112:115], v[140:143], v[228:231], v[112:115]
	v_mfma_f32_16x16x32_f16 v[108:111], v[148:151], v[228:231], v[108:111]
	v_mfma_f32_16x16x32_f16 v[104:107], v[140:143], v[236:239], v[104:107]
	v_mfma_f32_16x16x32_f16 v[100:103], v[148:151], v[236:239], v[100:103]
	s_setprio 0
	s_setprio 1
	v_mfma_f32_16x16x32_f16 v[96:99], v[152:155], v[168:171], v[96:99]
	v_mfma_f32_16x16x32_f16 v[92:95], v[160:163], v[168:171], v[92:95]
	v_mfma_f32_16x16x32_f16 v[88:91], v[152:155], v[176:179], v[88:91]
	v_mfma_f32_16x16x32_f16 v[84:87], v[160:163], v[176:179], v[84:87]
	v_mfma_f32_16x16x32_f16 v[80:83], v[152:155], v[224:227], v[80:83]
	v_mfma_f32_16x16x32_f16 v[76:79], v[160:163], v[224:227], v[76:79]
	v_mfma_f32_16x16x32_f16 v[72:75], v[152:155], v[232:235], v[72:75]
	v_mfma_f32_16x16x32_f16 v[68:71], v[160:163], v[232:235], v[68:71]
	v_mfma_f32_16x16x32_f16 v[96:99], v[156:159], v[172:175], v[96:99]
	v_mfma_f32_16x16x32_f16 v[92:95], v[164:167], v[172:175], v[92:95]
	v_mfma_f32_16x16x32_f16 v[88:91], v[156:159], v[206:209], v[88:91]
	v_mfma_f32_16x16x32_f16 v[84:87], v[164:167], v[206:209], v[84:87]
	v_mfma_f32_16x16x32_f16 v[80:83], v[156:159], v[228:231], v[80:83]
	v_mfma_f32_16x16x32_f16 v[76:79], v[164:167], v[228:231], v[76:79]
	v_mfma_f32_16x16x32_f16 v[72:75], v[156:159], v[236:239], v[72:75]
	v_mfma_f32_16x16x32_f16 v[68:71], v[164:167], v[236:239], v[68:71]
	s_setprio 0
	s_barrier
; #define PG8_STAGE(bufoff, gbase, voff) do { _Pragma("unroll") for (int _i = 0; _i < 2; ++_i) \
;         __builtin_amdgcn_global_load_lds((const unsigned*)((const char*)(gbase) + (voff)[_i]), (LAS unsigned*)(lds + (bufoff) + ldsw + _i * 8192), 16, 0, 0); } while (0)
; #define PG8_LDA(dst, b, h) do { _Pragma("unroll") for (int m = 0; m < 4; ++m) _Pragma("unroll") for (int k = 0; k < 2; ++k) dst[m][k] = *(const LAS h8*)(lds + PG8_SA(b, h) + aoff + m * 2048 + k * 1024); } while (0)
; #define PG8_MMA(ai, bj, At, Bt) do { __builtin_amdgcn_s_setprio(1); _Pragma("unroll") for (int m = 0; m < 4; ++m) _Pragma("unroll") for (int n = 0; n < 2; ++n) _Pragma("unroll") for (int k = 0; k < 2; ++k) \
;         acc[ai][bj][m][n] = __builtin_amdgcn_mfma_f32_16x16x32_f16(Bt[n][k], At[m][k], acc[ai][bj][m][n], 0, 0, 0); __builtin_amdgcn_s_setprio(0); } while (0)
; #define PG8_WAIT_V(n) asm volatile("s_waitcnt vmcnt(" #n ")" ::: "memory")
; #define PG8_WAIT_L(n) asm volatile("s_waitcnt lgkmcnt(" #n ")" ::: "memory")
; #define PG8_BAR __builtin_amdgcn_s_barrier()
; #define PG8_SCHED __builtin_amdgcn_sched_barrier(0)
; template <class Epi>
; __device__ __forceinline__ void gemm_phase(LAS unsigned char* lds, const Gemm g, const StaticOrder& S, const Epi& E, unsigned long long& sw_acc) {
;     ...
;             PG8_LDA(At, 0, 1); PG8_STAGE(PG8_SB(0, 0), b2, voffB); PG8_STAGE(PG8_SB(0, 1), b2 + hstepB, voffB); PG8_STAGE(PG8_SA(0, 0), a2, voffA);
;             PG8_WAIT_V(8); PG8_WAIT_L(0); PG8_BAR; PG8_MMA(1, 0, At, B0); PG8_MMA(1, 1, At, B1); PG8_BAR; PG8_SCHED;
	s_add_i32 s20, s21, s26
	v_lshl_add_u64 v[240:241], s[6:7], 0, v[196:197]
	s_mov_b32 m0, s20
	ds_read_b128 v[168:171], v221 offset:16384
	ds_read_b128 v[172:175], v221 offset:17408
	ds_read_b128 v[176:179], v221 offset:18432
	ds_read_b128 v[206:209], v221 offset:19456
	ds_read_b128 v[224:227], v221 offset:20480
	ds_read_b128 v[228:231], v221 offset:21504
	ds_read_b128 v[232:235], v221 offset:22528
	ds_read_b128 v[236:239], v221 offset:23552
	global_load_lds_dwordx4 v[240:241], off
	s_add_i32 m0, s20, 0x2000
	s_add_u32 s20, s6, 0x10000
	v_lshl_add_u64 v[242:243], s[6:7], 0, v[192:193]
	s_addc_u32 s21, s7, 0
	s_add_i32 s15, s15, s26
	global_load_lds_dwordx4 v[242:243], off
	v_lshl_add_u64 v[244:245], s[20:21], 0, v[196:197]
	s_mov_b32 m0, s15
	v_lshl_add_u64 v[246:247], s[18:19], 0, v[194:195]
	global_load_lds_dwordx4 v[244:245], off
	v_lshl_add_u64 v[244:245], s[20:21], 0, v[192:193]
	s_add_i32 m0, s15, 0x2000
	s_nop 0
	global_load_lds_dwordx4 v[244:245], off
	v_lshl_add_u64 v[244:245], s[18:19], 0, v[198:199]
	s_mov_b32 m0, s31
	s_nop 0
	global_load_lds_dwordx4 v[244:245], off
	s_mov_b32 m0, s33
	s_nop 0
	global_load_lds_dwordx4 v[246:247], off
	s_waitcnt vmcnt(24)
	s_waitcnt lgkmcnt(0)
	s_barrier
	s_setprio 1
	s_waitcnt lgkmcnt(0)
	v_mfma_f32_16x16x32_f16 v[64:67], v[136:139], v[168:171], v[64:67]
	v_mfma_f32_16x16x32_f16 v[60:63], v[144:147], v[168:171], v[60:63]
	v_mfma_f32_16x16x32_f16 v[56:59], v[136:139], v[176:179], v[56:59]
	v_mfma_f32_16x16x32_f16 v[52:55], v[144:147], v[176:179], v[52:55]
	v_mfma_f32_16x16x32_f16 v[48:51], v[136:139], v[224:227], v[48:51]
	v_mfma_f32_16x16x32_f16 v[44:47], v[144:147], v[224:227], v[44:47]
	v_mfma_f32_16x16x32_f16 v[40:43], v[136:139], v[232:235], v[40:43]
	v_mfma_f32_16x16x32_f16 v[36:39], v[144:147], v[232:235], v[36:39]
	v_mfma_f32_16x16x32_f16 v[64:67], v[140:143], v[172:175], v[64:67]
	v_mfma_f32_16x16x32_f16 v[60:63], v[148:151], v[172:175], v[60:63]
	v_mfma_f32_16x16x32_f16 v[56:59], v[140:143], v[206:209], v[56:59]
	v_mfma_f32_16x16x32_f16 v[52:55], v[148:151], v[206:209], v[52:55]
	v_mfma_f32_16x16x32_f16 v[48:51], v[140:143], v[228:231], v[48:51]
	v_mfma_f32_16x16x32_f16 v[44:47], v[148:151], v[228:231], v[44:47]
	v_mfma_f32_16x16x32_f16 v[40:43], v[140:143], v[236:239], v[40:43]
	v_mfma_f32_16x16x32_f16 v[36:39], v[148:151], v[236:239], v[36:39]
	s_setprio 0
	s_setprio 1
	v_mfma_f32_16x16x32_f16 v[32:35], v[152:155], v[168:171], v[32:35]
	v_mfma_f32_16x16x32_f16 v[28:31], v[160:163], v[168:171], v[28:31]
	v_mfma_f32_16x16x32_f16 v[24:27], v[152:155], v[176:179], v[24:27]
	v_mfma_f32_16x16x32_f16 v[20:23], v[160:163], v[176:179], v[20:23]
	v_mfma_f32_16x16x32_f16 v[16:19], v[152:155], v[224:227], v[16:19]
	v_mfma_f32_16x16x32_f16 v[12:15], v[160:163], v[224:227], v[12:15]
	v_mfma_f32_16x16x32_f16 v[8:11], v[152:155], v[232:235], v[8:11]
	v_mfma_f32_16x16x32_f16 v[4:7], v[160:163], v[232:235], v[4:7]
	v_mfma_f32_16x16x32_f16 v[32:35], v[156:159], v[172:175], v[32:35]
	v_mfma_f32_16x16x32_f16 v[28:31], v[164:167], v[172:175], v[28:31]
	v_mfma_f32_16x16x32_f16 v[24:27], v[156:159], v[206:209], v[24:27]
	v_mfma_f32_16x16x32_f16 v[20:23], v[164:167], v[206:209], v[20:23]
	v_mfma_f32_16x16x32_f16 v[16:19], v[156:159], v[228:231], v[16:19]
	v_mfma_f32_16x16x32_f16 v[12:15], v[164:167], v[228:231], v[12:15]
	v_mfma_f32_16x16x32_f16 v[8:11], v[156:159], v[236:239], v[8:11]
	v_mfma_f32_16x16x32_f16 v[4:7], v[164:167], v[236:239], v[4:7]
	s_setprio 0
	s_barrier
	s_branch .Lg1_mid

; #define PG8_STAGE(bufoff, gbase, voff) do { _Pragma("unroll") for (int _i = 0; _i < 2; ++_i) \
;         __builtin_amdgcn_global_load_lds((const unsigned*)((const char*)(gbase) + (voff)[_i]), (LAS unsigned*)(lds + (bufoff) + ldsw + _i * 8192), 16, 0, 0); } while (0)
; #define PG8_LDA(dst, b, h) do { _Pragma("unroll") for (int m = 0; m < 4; ++m) _Pragma("unroll") for (int k = 0; k < 2; ++k) dst[m][k] = *(const LAS h8*)(lds + PG8_SA(b, h) + aoff + m * 2048 + k * 1024); } while (0)
; #define PG8_LDB(dst, b, h) do { _Pragma("unroll") for (int n = 0; n < 2; ++n) _Pragma("unroll") for (int k = 0; k < 2; ++k) dst[n][k] = *(const LAS h8*)(lds + PG8_SB(b, h) + boff + n * 2048 + k * 1024); } while (0)
; #define PG8_MMA(ai, bj, At, Bt) do { __builtin_amdgcn_s_setprio(1); _Pragma("unroll") for (int m = 0; m < 4; ++m) _Pragma("unroll") for (int n = 0; n < 2; ++n) _Pragma("unroll") for (int k = 0; k < 2; ++k) \
;         acc[ai][bj][m][n] = __builtin_amdgcn_mfma_f32_16x16x32_f16(Bt[n][k], At[m][k], acc[ai][bj][m][n], 0, 0, 0); __builtin_amdgcn_s_setprio(0); } while (0)
; #define PG8_WAIT_V(n) asm volatile("s_waitcnt vmcnt(" #n ")" ::: "memory")
; #define PG8_WAIT_L(n) asm volatile("s_waitcnt lgkmcnt(" #n ")" ::: "memory")
; #define PG8_BAR __builtin_amdgcn_s_barrier()
; #define PG8_SCHED __builtin_amdgcn_sched_barrier(0)
; template <class Epi>
; __device__ __forceinline__ void gemm_phase(LAS unsigned char* lds, const Gemm g, const StaticOrder& S, const Epi& E, unsigned long long& sw_acc) {
;     ...
;             PG8_LDB(B0, 1, 0); PG8_LDB(B1, 1, 1); PG8_SCHED; PG8_LDA(At, 1, 0); PG8_STAGE(PG8_SA(0, 1), a2 + hstep, voffA);
;             PG8_WAIT_V(8); PG8_WAIT_L(0); PG8_BAR; PG8_MMA(0, 0, At, B0); PG8_MMA(0, 1, At, B1); PG8_BAR; PG8_SCHED;
.Lg1_mid:
	s_add_i32 s15, 0, 0x18000
	v_add_u32_e32 v2, s15, v218
	s_add_i32 s20, 0, 0x1c000
	ds_read_b128 v[136:139], v2
	ds_read_b128 v[140:143], v2 offset:1024
	ds_read_b128 v[144:147], v2 offset:2048
	ds_read_b128 v[148:151], v2 offset:3072
	v_add_u32_e32 v2, s20, v218
	ds_read_b128 v[152:155], v2
	ds_read_b128 v[156:159], v2 offset:1024
	ds_read_b128 v[160:163], v2 offset:2048
	ds_read_b128 v[164:167], v2 offset:3072
	s_add_u32 s18, s18, 0x40000
	s_addc_u32 s19, s19, 0
	s_mov_b32 m0, s34
	v_lshl_add_u64 v[248:249], s[18:19], 0, v[198:199]
	ds_read_b128 v[168:171], v221 offset:32768
	ds_read_b128 v[172:175], v221 offset:33792
	ds_read_b128 v[176:179], v221 offset:34816
	ds_read_b128 v[206:209], v221 offset:35840
	ds_read_b128 v[224:227], v221 offset:36864
	ds_read_b128 v[228:231], v221 offset:37888
	ds_read_b128 v[232:235], v221 offset:38912
	ds_read_b128 v[236:239], v221 offset:39936
	global_load_lds_dwordx4 v[248:249], off
	v_lshl_add_u64 v[248:249], s[18:19], 0, v[194:195]
	s_mov_b32 m0, s35
	s_nop 0
	global_load_lds_dwordx4 v[248:249], off
	s_waitcnt vmcnt(8)
	s_waitcnt lgkmcnt(0)
	s_barrier
	s_setprio 1
	s_waitcnt lgkmcnt(0)
	v_mfma_f32_16x16x32_f16 v[128:131], v[136:139], v[168:171], v[128:131]
	v_mfma_f32_16x16x32_f16 v[124:127], v[144:147], v[168:171], v[124:127]
	v_mfma_f32_16x16x32_f16 v[120:123], v[136:139], v[176:179], v[120:123]
	v_mfma_f32_16x16x32_f16 v[116:119], v[144:147], v[176:179], v[116:119]
	v_mfma_f32_16x16x32_f16 v[112:115], v[136:139], v[224:227], v[112:115]
	v_mfma_f32_16x16x32_f16 v[108:111], v[144:147], v[224:227], v[108:111]
	v_mfma_f32_16x16x32_f16 v[104:107], v[136:139], v[232:235], v[104:107]
	v_mfma_f32_16x16x32_f16 v[100:103], v[144:147], v[232:235], v[100:103]
	v_mfma_f32_16x16x32_f16 v[128:131], v[140:143], v[172:175], v[128:131]
	v_mfma_f32_16x16x32_f16 v[124:127], v[148:151], v[172:175], v[124:127]
	v_mfma_f32_16x16x32_f16 v[120:123], v[140:143], v[206:209], v[120:123]
	v_mfma_f32_16x16x32_f16 v[116:119], v[148:151], v[206:209], v[116:119]
	v_mfma_f32_16x16x32_f16 v[112:115], v[140:143], v[228:231], v[112:115]
	v_mfma_f32_16x16x32_f16 v[108:111], v[148:151], v[228:231], v[108:111]
	v_mfma_f32_16x16x32_f16 v[104:107], v[140:143], v[236:239], v[104:107]
	v_mfma_f32_16x16x32_f16 v[100:103], v[148:151], v[236:239], v[100:103]
	s_setprio 0
	s_setprio 1
	v_mfma_f32_16x16x32_f16 v[96:99], v[152:155], v[168:171], v[96:99]
	v_mfma_f32_16x16x32_f16 v[92:95], v[160:163], v[168:171], v[92:95]
	v_mfma_f32_16x16x32_f16 v[88:91], v[152:155], v[176:179], v[88:91]
	v_mfma_f32_16x16x32_f16 v[84:87], v[160:163], v[176:179], v[84:87]
	v_mfma_f32_16x16x32_f16 v[80:83], v[152:155], v[224:227], v[80:83]
	v_mfma_f32_16x16x32_f16 v[76:79], v[160:163], v[224:227], v[76:79]
	v_mfma_f32_16x16x32_f16 v[72:75], v[152:155], v[232:235], v[72:75]
	v_mfma_f32_16x16x32_f16 v[68:71], v[160:163], v[232:235], v[68:71]
	v_mfma_f32_16x16x32_f16 v[96:99], v[156:159], v[172:175], v[96:99]
	v_mfma_f32_16x16x32_f16 v[92:95], v[164:167], v[172:175], v[92:95]
	v_mfma_f32_16x16x32_f16 v[88:91], v[156:159], v[206:209], v[88:91]
	v_mfma_f32_16x16x32_f16 v[84:87], v[164:167], v[206:209], v[84:87]
	v_mfma_f32_16x16x32_f16 v[80:83], v[156:159], v[228:231], v[80:83]
	v_mfma_f32_16x16x32_f16 v[76:79], v[164:167], v[228:231], v[76:79]
	v_mfma_f32_16x16x32_f16 v[72:75], v[156:159], v[236:239], v[72:75]
	v_mfma_f32_16x16x32_f16 v[68:71], v[164:167], v[236:239], v[68:71]
	s_setprio 0
	s_barrier
; #define PG8_STAGE(bufoff, gbase, voff) do { _Pragma("unroll") for (int _i = 0; _i < 2; ++_i) \
;         __builtin_amdgcn_global_load_lds((const unsigned*)((const char*)(gbase) + (voff)[_i]), (LAS unsigned*)(lds + (bufoff) + ldsw + _i * 8192), 16, 0, 0); } while (0)
; #define PG8_LDA(dst, b, h) do { _Pragma("unroll") for (int m = 0; m < 4; ++m) _Pragma("unroll") for (int k = 0; k < 2; ++k) dst[m][k] = *(const LAS h8*)(lds + PG8_SA(b, h) + aoff + m * 2048 + k * 1024); } while (0)
; #define PG8_MMA(ai, bj, At, Bt) do { __builtin_amdgcn_s_setprio(1); _Pragma("unroll") for (int m = 0; m < 4; ++m) _Pragma("unroll") for (int n = 0; n < 2; ++n) _Pragma("unroll") for (int k = 0; k < 2; ++k) \
;         acc[ai][bj][m][n] = __builtin_amdgcn_mfma_f32_16x16x32_f16(Bt[n][k], At[m][k], acc[ai][bj][m][n], 0, 0, 0); __builtin_amdgcn_s_setprio(0); } while (0)
; #define PG8_WAIT_V(n) asm volatile("s_waitcnt vmcnt(" #n ")" ::: "memory")
; #define PG8_WAIT_L(n) asm volatile("s_waitcnt lgkmcnt(" #n ")" ::: "memory")
; #define PG8_BAR __builtin_amdgcn_s_barrier()
; #define PG8_SCHED __builtin_amdgcn_sched_barrier(0)
; template <class Epi>
; __device__ __forceinline__ void gemm_phase(LAS unsigned char* lds, const Gemm g, const StaticOrder& S, const Epi& E, unsigned long long& sw_acc) {
;     ...
;             PG8_LDA(At, 1, 1); PG8_STAGE(PG8_SB(1, 0), b3, voffB); PG8_STAGE(PG8_SB(1, 1), b3 + hstepB, voffB); PG8_STAGE(PG8_SA(1, 0), a3, voffA);
;             PG8_WAIT_V(8); PG8_WAIT_L(0); PG8_BAR; PG8_MMA(1, 0, At, B0); PG8_MMA(1, 1, At, B1); PG8_BAR; PG8_SCHED;
;         }
;         if (wr == 0) PG8_BAR;
	s_add_i32 s15, s15, s26
	v_lshl_add_u64 v[240:241], v[240:241], 0, s[16:17]
	s_mov_b32 m0, s15
	ds_read_b128 v[168:171], v221 offset:49152
	ds_read_b128 v[172:175], v221 offset:50176
	ds_read_b128 v[176:179], v221 offset:51200
	ds_read_b128 v[206:209], v221 offset:52224
	ds_read_b128 v[224:227], v221 offset:53248
	ds_read_b128 v[228:231], v221 offset:54272
	ds_read_b128 v[232:235], v221 offset:55296
	ds_read_b128 v[236:239], v221 offset:56320
	global_load_lds_dwordx4 v[240:241], off
	s_add_i32 m0, s15, 0x2000
	s_add_u32 s6, s6, 0x10080
	v_lshl_add_u64 v[240:241], v[242:243], 0, s[16:17]
	s_addc_u32 s7, s7, 0
	s_add_i32 s15, s20, s26
	global_load_lds_dwordx4 v[240:241], off
	v_lshl_add_u64 v[240:241], s[6:7], 0, v[196:197]
	s_mov_b32 m0, s15
	s_nop 0
	global_load_lds_dwordx4 v[240:241], off
	v_lshl_add_u64 v[240:241], s[6:7], 0, v[192:193]
	s_add_i32 m0, s15, 0x2000
	s_nop 0
	global_load_lds_dwordx4 v[240:241], off
	v_lshl_add_u64 v[240:241], v[244:245], 0, s[16:17]
	s_mov_b32 m0, s36
	s_nop 0
	global_load_lds_dwordx4 v[240:241], off
	v_lshl_add_u64 v[240:241], v[246:247], 0, s[16:17]
	s_mov_b32 m0, s37
	s_nop 0
	global_load_lds_dwordx4 v[240:241], off
	s_waitcnt vmcnt(8)
	s_waitcnt lgkmcnt(0)
	s_barrier
	s_setprio 1
	s_waitcnt lgkmcnt(0)
	v_mfma_f32_16x16x32_f16 v[64:67], v[136:139], v[168:171], v[64:67]
	v_mfma_f32_16x16x32_f16 v[60:63], v[144:147], v[168:171], v[60:63]
	v_mfma_f32_16x16x32_f16 v[56:59], v[136:139], v[176:179], v[56:59]
	v_mfma_f32_16x16x32_f16 v[52:55], v[144:147], v[176:179], v[52:55]
	v_mfma_f32_16x16x32_f16 v[48:51], v[136:139], v[224:227], v[48:51]
	v_mfma_f32_16x16x32_f16 v[44:47], v[144:147], v[224:227], v[44:47]
	v_mfma_f32_16x16x32_f16 v[40:43], v[136:139], v[232:235], v[40:43]
	v_mfma_f32_16x16x32_f16 v[36:39], v[144:147], v[232:235], v[36:39]
	v_mfma_f32_16x16x32_f16 v[64:67], v[140:143], v[172:175], v[64:67]
	v_mfma_f32_16x16x32_f16 v[60:63], v[148:151], v[172:175], v[60:63]
	v_mfma_f32_16x16x32_f16 v[56:59], v[140:143], v[206:209], v[56:59]
	v_mfma_f32_16x16x32_f16 v[52:55], v[148:151], v[206:209], v[52:55]
	v_mfma_f32_16x16x32_f16 v[48:51], v[140:143], v[228:231], v[48:51]
	v_mfma_f32_16x16x32_f16 v[44:47], v[148:151], v[228:231], v[44:47]
	v_mfma_f32_16x16x32_f16 v[40:43], v[140:143], v[236:239], v[40:43]
	v_mfma_f32_16x16x32_f16 v[36:39], v[148:151], v[236:239], v[36:39]
	s_setprio 0
	s_setprio 1
	v_mfma_f32_16x16x32_f16 v[32:35], v[152:155], v[168:171], v[32:35]
	v_mfma_f32_16x16x32_f16 v[28:31], v[160:163], v[168:171], v[28:31]
	v_mfma_f32_16x16x32_f16 v[24:27], v[152:155], v[176:179], v[24:27]
	v_mfma_f32_16x16x32_f16 v[20:23], v[160:163], v[176:179], v[20:23]
	v_mfma_f32_16x16x32_f16 v[16:19], v[152:155], v[224:227], v[16:19]
	v_mfma_f32_16x16x32_f16 v[12:15], v[160:163], v[224:227], v[12:15]
	v_mfma_f32_16x16x32_f16 v[8:11], v[152:155], v[232:235], v[8:11]
	v_mfma_f32_16x16x32_f16 v[4:7], v[160:163], v[232:235], v[4:7]
	v_mfma_f32_16x16x32_f16 v[32:35], v[156:159], v[172:175], v[32:35]
	v_mfma_f32_16x16x32_f16 v[28:31], v[164:167], v[172:175], v[28:31]
	v_mfma_f32_16x16x32_f16 v[24:27], v[156:159], v[206:209], v[24:27]
	v_mfma_f32_16x16x32_f16 v[20:23], v[164:167], v[206:209], v[20:23]
	v_mfma_f32_16x16x32_f16 v[16:19], v[156:159], v[228:231], v[16:19]
	v_mfma_f32_16x16x32_f16 v[12:15], v[164:167], v[228:231], v[12:15]
	v_mfma_f32_16x16x32_f16 v[8:11], v[156:159], v[236:239], v[8:11]
	v_mfma_f32_16x16x32_f16 v[4:7], v[164:167], v[236:239], v[4:7]
	s_setprio 0
	s_barrier
	s_add_i32 s14, s14, 2
	s_add_u32 s4, s4, 0x100
	s_addc_u32 s5, s5, 0
	s_cmp_gt_u32 s14, 13
	s_cbranch_scc0 .LBB0_134
	s_and_b64 vcc, exec, s[54:55]
	s_cbranch_vccz .LBB0_137
	s_barrier
